# all three GEMM k-loops use the hand-pipelined rolled loop; phase_local GLA-increment GLOG loads batched
# baseline (speedup 1.0000x reference)
.LBB0_77:
	s_and_b32 s4, s0, 0xffffffc0
	s_sub_i32 s5, s4, 64
	v_mov_b32_e32 v6, s5
	v_mov_b32_e32 v7, s4
	v_cndmask_b32_e64 v4, v6, v7, s[36:37]
	v_add_u32_e32 v4, v4, v86
	v_ashrrev_i32_e32 v5, 31, v4
	v_lshlrev_b64 v[4:5], 11, v[4:5]
	s_lshl_b32 s1, s0, 7
	v_lshl_add_u64 v[84:85], v[68:69], 0, v[4:5]
	v_cndmask_b32_e64 v4, v6, v7, s[38:39]
	s_and_b32 s1, s1, 0x1f80
	v_add_u32_e32 v4, v90, v4
	v_add_u32_e32 v2, s1, v86
	v_ashrrev_i32_e32 v5, 31, v4
	v_ashrrev_i32_e32 v3, 31, v2
	v_lshlrev_b64 v[4:5], 11, v[4:5]
	v_lshlrev_b64 v[2:3], 11, v[2:3]
	v_lshl_add_u64 v[82:83], v[70:71], 0, v[4:5]
	v_add_u32_e32 v4, s4, v93
	v_readfirstlane_b32 s27, v92
	v_add_u32_e32 v114, 0x8000, v92
	v_ashrrev_i32_e32 v5, 31, v4
	v_lshl_add_u64 v[78:79], v[66:67], 0, v[2:3]
	s_mov_b32 m0, s27
	v_readfirstlane_b32 s44, v114
	v_add_u32_e32 v115, 0x1000, v92
	v_lshlrev_b64 v[4:5], 11, v[4:5]
	global_load_lds_dwordx4 v[78:79], off
	s_mov_b32 m0, s44
	v_readfirstlane_b32 s45, v115
	v_add_u32_e32 v116, 0x9000, v92
	v_lshl_add_u64 v[80:81], v[72:73], 0, v[4:5]
	v_cndmask_b32_e64 v4, v6, v7, s[40:41]
	global_load_lds_dwordx4 v[84:85], off
	v_lshl_add_u64 v[2:3], v[78:79], 0, s[96:97]
	s_mov_b32 m0, s45
	v_readfirstlane_b32 s46, v116
	v_add_u32_e32 v117, 0x2000, v92
	v_add_u32_e32 v4, v91, v4
	global_load_lds_dwordx4 v[2:3], off
	s_mov_b32 m0, s46
	s_mov_b64 s[6:7], 0x20000
	v_readfirstlane_b32 s47, v117
	v_add_u32_e32 v113, 0xa000, v92
	v_ashrrev_i32_e32 v5, 31, v4
	global_load_lds_dwordx4 v[82:83], off
	v_lshl_add_u64 v[2:3], v[78:79], 0, s[6:7]
	s_mov_b32 m0, s47
	v_readfirstlane_b32 s43, v113
	v_add_u32_e32 v112, 0x3000, v92
	v_lshlrev_b64 v[4:5], 11, v[4:5]
	global_load_lds_dwordx4 v[2:3], off
	s_mov_b32 m0, s43
	s_mov_b64 s[6:7], 0x30000
	v_readfirstlane_b32 s42, v112
	v_add_u32_e32 v109, 0xb000, v92
	v_lshl_add_u64 v[76:77], v[74:75], 0, v[4:5]
	global_load_lds_dwordx4 v[80:81], off
	v_lshl_add_u64 v[2:3], v[78:79], 0, s[6:7]
	s_mov_b32 m0, s42
	v_readfirstlane_b32 s16, v109
	v_add_u32_e32 v4, 0x4000, v92
	global_load_lds_dwordx4 v[2:3], off
	s_mov_b32 m0, s16
	v_readfirstlane_b32 s5, v4
	v_add_u32_e32 v4, 0xc000, v92
	global_load_lds_dwordx4 v[76:77], off
	v_lshl_add_u64 v[2:3], v[78:79], 0, s[98:99]
	s_mov_b32 m0, s5
	v_readfirstlane_b32 s6, v4
	v_add_u32_e32 v4, 0x5000, v92
	s_waitcnt vmcnt(0)
	s_waitcnt vmcnt(0) lgkmcnt(0)
	s_barrier
	v_mov_b32_e32 v2, 0
	v_mov_b32_e32 v3, 0
	v_mov_b32_e32 v4, 0
	v_mov_b32_e32 v5, 0
	v_mov_b32_e32 v6, 0
	v_mov_b32_e32 v7, 0
	v_mov_b32_e32 v8, 0
	v_mov_b32_e32 v9, 0
	v_mov_b32_e32 v10, 0
	v_mov_b32_e32 v11, 0
	v_mov_b32_e32 v12, 0
	v_mov_b32_e32 v13, 0
	v_mov_b32_e32 v14, 0
	v_mov_b32_e32 v15, 0
	v_mov_b32_e32 v16, 0
	v_mov_b32_e32 v17, 0
	v_mov_b32_e32 v18, 0
	v_mov_b32_e32 v19, 0
	v_mov_b32_e32 v20, 0
	v_mov_b32_e32 v21, 0
	v_mov_b32_e32 v22, 0
	v_mov_b32_e32 v23, 0
	v_mov_b32_e32 v24, 0
	v_mov_b32_e32 v25, 0
	v_mov_b32_e32 v26, 0
	v_mov_b32_e32 v27, 0
	v_mov_b32_e32 v28, 0
	v_mov_b32_e32 v29, 0
	v_mov_b32_e32 v30, 0
	v_mov_b32_e32 v31, 0
	v_mov_b32_e32 v32, 0
	v_mov_b32_e32 v33, 0
	v_mov_b32_e32 v34, 0
	v_mov_b32_e32 v35, 0
	v_mov_b32_e32 v36, 0
	v_mov_b32_e32 v37, 0
	v_mov_b32_e32 v38, 0
	v_mov_b32_e32 v39, 0
	v_mov_b32_e32 v40, 0
	v_mov_b32_e32 v41, 0
	v_mov_b32_e32 v42, 0
	v_mov_b32_e32 v43, 0
	v_mov_b32_e32 v44, 0
	v_mov_b32_e32 v45, 0
	v_mov_b32_e32 v46, 0
	v_mov_b32_e32 v47, 0
	v_mov_b32_e32 v48, 0
	v_mov_b32_e32 v49, 0
	v_mov_b32_e32 v50, 0
	v_mov_b32_e32 v51, 0
	v_mov_b32_e32 v52, 0
	v_mov_b32_e32 v53, 0
	v_mov_b32_e32 v54, 0
	v_mov_b32_e32 v55, 0
	v_mov_b32_e32 v56, 0
	v_mov_b32_e32 v57, 0
	v_mov_b32_e32 v58, 0
	v_mov_b32_e32 v59, 0
	v_mov_b32_e32 v60, 0
	v_mov_b32_e32 v61, 0
	v_mov_b32_e32 v62, 0
	v_mov_b32_e32 v63, 0
	v_mov_b32_e32 v64, 0
	v_mov_b32_e32 v65, 0
	v_lshl_add_u64 v[160:161], v[78:79], 0, s[98:99]
	s_mov_b64 s[10:11], 0x10080
	v_lshl_add_u64 v[162:163], v[78:79], 0, s[10:11]
	s_mov_b64 s[10:11], 0x20080
	v_lshl_add_u64 v[164:165], v[78:79], 0, s[10:11]
	s_mov_b64 s[10:11], 0x30080
	v_lshl_add_u64 v[166:167], v[78:79], 0, s[10:11]
	v_lshl_add_u64 v[168:169], v[84:85], 0, s[98:99]
	v_lshl_add_u64 v[170:171], v[82:83], 0, s[98:99]
	v_lshl_add_u64 v[172:173], v[80:81], 0, s[98:99]
	v_lshl_add_u64 v[174:175], v[76:77], 0, s[98:99]
	v_add_u32_e32 v222, v96, v89
	v_add_u32_e32 v223, v95, v89
	v_add_u32_e32 v224, v94, v89
	v_add_u32_e32 v225, v87, v89
	s_mov_b32 s44, 7
	ds_read_b128 v[176:179], v98
	ds_read_b128 v[180:183], v98 offset:4096
	ds_read_b128 v[184:187], v222 offset:32768
	ds_read_b128 v[188:191], v222 offset:40960
.Lg1_loop:
	ds_read_b128 v[206:209], v99
	ds_read_b128 v[210:213], v99 offset:4096
	ds_read_b128 v[214:217], v223 offset:32768
	ds_read_b128 v[218:221], v223 offset:40960
	s_waitcnt lgkmcnt(4)
	v_mfma_f32_32x32x16_bf16 v[34:49], v[176:179], v[184:187], v[34:49]
	s_add_u32 m0, s27, 0x4000
	s_nop 0
	global_load_lds_dwordx4 v[160:161], off
	v_lshl_add_u64 v[160:161], v[160:161], 0, s[98:99]
	v_mfma_f32_32x32x16_bf16 v[50:65], v[176:179], v[188:191], v[50:65]
	s_add_u32 m0, s27, 0xc000
	s_nop 0
	global_load_lds_dwordx4 v[168:169], off
	v_lshl_add_u64 v[168:169], v[168:169], 0, s[98:99]
	v_mfma_f32_32x32x16_bf16 v[2:17], v[180:183], v[184:187], v[2:17]
	s_add_u32 m0, s27, 0x5000
	s_nop 0
	global_load_lds_dwordx4 v[162:163], off
	v_lshl_add_u64 v[162:163], v[162:163], 0, s[98:99]
	v_mfma_f32_32x32x16_bf16 v[18:33], v[180:183], v[188:191], v[18:33]
	ds_read_b128 v[176:179], v100
	ds_read_b128 v[180:183], v100 offset:4096
	ds_read_b128 v[184:187], v224 offset:32768
	ds_read_b128 v[188:191], v224 offset:40960
	s_waitcnt lgkmcnt(4)
	v_mfma_f32_32x32x16_bf16 v[34:49], v[206:209], v[214:217], v[34:49]
	s_add_u32 m0, s27, 0xd000
	s_nop 0
	global_load_lds_dwordx4 v[170:171], off
	v_lshl_add_u64 v[170:171], v[170:171], 0, s[98:99]
	v_mfma_f32_32x32x16_bf16 v[50:65], v[206:209], v[218:221], v[50:65]
	s_add_u32 m0, s27, 0x6000
	s_nop 0
	global_load_lds_dwordx4 v[164:165], off
	v_lshl_add_u64 v[164:165], v[164:165], 0, s[98:99]
	v_mfma_f32_32x32x16_bf16 v[2:17], v[210:213], v[214:217], v[2:17]
	s_add_u32 m0, s27, 0xe000
	s_nop 0
	global_load_lds_dwordx4 v[172:173], off
	v_lshl_add_u64 v[172:173], v[172:173], 0, s[98:99]
	v_mfma_f32_32x32x16_bf16 v[18:33], v[210:213], v[218:221], v[18:33]
	ds_read_b128 v[206:209], v101
	ds_read_b128 v[210:213], v101 offset:4096
	ds_read_b128 v[214:217], v225 offset:32768
	ds_read_b128 v[218:221], v225 offset:40960
	s_waitcnt lgkmcnt(4)
	v_mfma_f32_32x32x16_bf16 v[34:49], v[176:179], v[184:187], v[34:49]
	s_add_u32 m0, s27, 0x7000
	s_nop 0
	global_load_lds_dwordx4 v[166:167], off
	v_lshl_add_u64 v[166:167], v[166:167], 0, s[98:99]
	v_mfma_f32_32x32x16_bf16 v[50:65], v[176:179], v[188:191], v[50:65]
	s_add_u32 m0, s27, 0xf000
	s_nop 0
	global_load_lds_dwordx4 v[174:175], off
	v_lshl_add_u64 v[174:175], v[174:175], 0, s[98:99]
	v_mfma_f32_32x32x16_bf16 v[2:17], v[180:183], v[184:187], v[2:17]
	v_mfma_f32_32x32x16_bf16 v[18:33], v[180:183], v[188:191], v[18:33]
	s_waitcnt vmcnt(0) lgkmcnt(0)
	s_barrier
	ds_read_b128 v[176:179], v98 offset:16384
	ds_read_b128 v[180:183], v98 offset:20480
	ds_read_b128 v[184:187], v222 offset:49152
	ds_read_b128 v[188:191], v222 offset:57344
	v_mfma_f32_32x32x16_bf16 v[34:49], v[206:209], v[214:217], v[34:49]
	v_mfma_f32_32x32x16_bf16 v[50:65], v[206:209], v[218:221], v[50:65]
	v_mfma_f32_32x32x16_bf16 v[2:17], v[210:213], v[214:217], v[2:17]
	v_mfma_f32_32x32x16_bf16 v[18:33], v[210:213], v[218:221], v[18:33]
	ds_read_b128 v[206:209], v99 offset:16384
	ds_read_b128 v[210:213], v99 offset:20480
	ds_read_b128 v[214:217], v223 offset:49152
	ds_read_b128 v[218:221], v223 offset:57344
	s_waitcnt lgkmcnt(4)
	v_mfma_f32_32x32x16_bf16 v[34:49], v[176:179], v[184:187], v[34:49]
	s_mov_b32 m0, s27
	s_nop 0
	global_load_lds_dwordx4 v[160:161], off
	v_lshl_add_u64 v[160:161], v[160:161], 0, s[98:99]
	v_mfma_f32_32x32x16_bf16 v[50:65], v[176:179], v[188:191], v[50:65]
	s_add_u32 m0, s27, 0x8000
	s_nop 0
	global_load_lds_dwordx4 v[168:169], off
	v_lshl_add_u64 v[168:169], v[168:169], 0, s[98:99]
	v_mfma_f32_32x32x16_bf16 v[2:17], v[180:183], v[184:187], v[2:17]
	s_add_u32 m0, s27, 0x1000
	s_nop 0
	global_load_lds_dwordx4 v[162:163], off
	v_lshl_add_u64 v[162:163], v[162:163], 0, s[98:99]
	v_mfma_f32_32x32x16_bf16 v[18:33], v[180:183], v[188:191], v[18:33]
	ds_read_b128 v[176:179], v100 offset:16384
	ds_read_b128 v[180:183], v100 offset:20480
	ds_read_b128 v[184:187], v224 offset:49152
	ds_read_b128 v[188:191], v224 offset:57344
	s_waitcnt lgkmcnt(4)
	v_mfma_f32_32x32x16_bf16 v[34:49], v[206:209], v[214:217], v[34:49]
	s_add_u32 m0, s27, 0x9000
	s_nop 0
	global_load_lds_dwordx4 v[170:171], off
	v_lshl_add_u64 v[170:171], v[170:171], 0, s[98:99]
	v_mfma_f32_32x32x16_bf16 v[50:65], v[206:209], v[218:221], v[50:65]
	s_add_u32 m0, s27, 0x2000
	s_nop 0
	global_load_lds_dwordx4 v[164:165], off
	v_lshl_add_u64 v[164:165], v[164:165], 0, s[98:99]
	v_mfma_f32_32x32x16_bf16 v[2:17], v[210:213], v[214:217], v[2:17]
	s_add_u32 m0, s27, 0xa000
	s_nop 0
	global_load_lds_dwordx4 v[172:173], off
	v_lshl_add_u64 v[172:173], v[172:173], 0, s[98:99]
	v_mfma_f32_32x32x16_bf16 v[18:33], v[210:213], v[218:221], v[18:33]
	ds_read_b128 v[206:209], v101 offset:16384
	ds_read_b128 v[210:213], v101 offset:20480
	ds_read_b128 v[214:217], v225 offset:49152
	ds_read_b128 v[218:221], v225 offset:57344
	s_waitcnt lgkmcnt(4)
	v_mfma_f32_32x32x16_bf16 v[34:49], v[176:179], v[184:187], v[34:49]
	s_add_u32 m0, s27, 0x3000
	s_nop 0
	global_load_lds_dwordx4 v[166:167], off
	v_lshl_add_u64 v[166:167], v[166:167], 0, s[98:99]
	v_mfma_f32_32x32x16_bf16 v[50:65], v[176:179], v[188:191], v[50:65]
	s_add_u32 m0, s27, 0xb000
	s_nop 0
	global_load_lds_dwordx4 v[174:175], off
	v_lshl_add_u64 v[174:175], v[174:175], 0, s[98:99]
	v_mfma_f32_32x32x16_bf16 v[2:17], v[180:183], v[184:187], v[2:17]
	v_mfma_f32_32x32x16_bf16 v[18:33], v[180:183], v[188:191], v[18:33]
	s_waitcnt vmcnt(0) lgkmcnt(0)
	s_barrier
	ds_read_b128 v[176:179], v98
	ds_read_b128 v[180:183], v98 offset:4096
	ds_read_b128 v[184:187], v222 offset:32768
	ds_read_b128 v[188:191], v222 offset:40960
	v_mfma_f32_32x32x16_bf16 v[34:49], v[206:209], v[214:217], v[34:49]
	v_mfma_f32_32x32x16_bf16 v[50:65], v[206:209], v[218:221], v[50:65]
	v_mfma_f32_32x32x16_bf16 v[2:17], v[210:213], v[214:217], v[2:17]
	v_mfma_f32_32x32x16_bf16 v[18:33], v[210:213], v[218:221], v[18:33]
	s_sub_u32 s44, s44, 1
	s_cmp_lg_u32 s44, 0
	s_cbranch_scc1 .Lg1_loop
	ds_read_b128 v[206:209], v99
	ds_read_b128 v[210:213], v99 offset:4096
	ds_read_b128 v[214:217], v223 offset:32768
	ds_read_b128 v[218:221], v223 offset:40960
	s_waitcnt lgkmcnt(4)
	v_mfma_f32_32x32x16_bf16 v[34:49], v[176:179], v[184:187], v[34:49]
	s_add_u32 m0, s27, 0x4000
	s_nop 0
	global_load_lds_dwordx4 v[160:161], off
	v_lshl_add_u64 v[160:161], v[160:161], 0, s[98:99]
	v_mfma_f32_32x32x16_bf16 v[50:65], v[176:179], v[188:191], v[50:65]
	s_add_u32 m0, s27, 0xc000
	s_nop 0
	global_load_lds_dwordx4 v[168:169], off
	v_lshl_add_u64 v[168:169], v[168:169], 0, s[98:99]
	v_mfma_f32_32x32x16_bf16 v[2:17], v[180:183], v[184:187], v[2:17]
	s_add_u32 m0, s27, 0x5000
	s_nop 0
	global_load_lds_dwordx4 v[162:163], off
	v_lshl_add_u64 v[162:163], v[162:163], 0, s[98:99]
	v_mfma_f32_32x32x16_bf16 v[18:33], v[180:183], v[188:191], v[18:33]
	ds_read_b128 v[176:179], v100
	ds_read_b128 v[180:183], v100 offset:4096
	ds_read_b128 v[184:187], v224 offset:32768
	ds_read_b128 v[188:191], v224 offset:40960
	s_waitcnt lgkmcnt(4)
	v_mfma_f32_32x32x16_bf16 v[34:49], v[206:209], v[214:217], v[34:49]
	s_add_u32 m0, s27, 0xd000
	s_nop 0
	global_load_lds_dwordx4 v[170:171], off
	v_lshl_add_u64 v[170:171], v[170:171], 0, s[98:99]
	v_mfma_f32_32x32x16_bf16 v[50:65], v[206:209], v[218:221], v[50:65]
	s_add_u32 m0, s27, 0x6000
	s_nop 0
	global_load_lds_dwordx4 v[164:165], off
	v_lshl_add_u64 v[164:165], v[164:165], 0, s[98:99]
	v_mfma_f32_32x32x16_bf16 v[2:17], v[210:213], v[214:217], v[2:17]
	s_add_u32 m0, s27, 0xe000
	s_nop 0
	global_load_lds_dwordx4 v[172:173], off
	v_lshl_add_u64 v[172:173], v[172:173], 0, s[98:99]
	v_mfma_f32_32x32x16_bf16 v[18:33], v[210:213], v[218:221], v[18:33]
	ds_read_b128 v[206:209], v101
	ds_read_b128 v[210:213], v101 offset:4096
	ds_read_b128 v[214:217], v225 offset:32768
	ds_read_b128 v[218:221], v225 offset:40960
	s_waitcnt lgkmcnt(4)
	v_mfma_f32_32x32x16_bf16 v[34:49], v[176:179], v[184:187], v[34:49]
	s_add_u32 m0, s27, 0x7000
	s_nop 0
	global_load_lds_dwordx4 v[166:167], off
	v_lshl_add_u64 v[166:167], v[166:167], 0, s[98:99]
	v_mfma_f32_32x32x16_bf16 v[50:65], v[176:179], v[188:191], v[50:65]
	s_add_u32 m0, s27, 0xf000
	s_nop 0
	global_load_lds_dwordx4 v[174:175], off
	v_lshl_add_u64 v[174:175], v[174:175], 0, s[98:99]
	v_mfma_f32_32x32x16_bf16 v[2:17], v[180:183], v[184:187], v[2:17]
	v_mfma_f32_32x32x16_bf16 v[18:33], v[180:183], v[188:191], v[18:33]
	s_waitcnt vmcnt(0) lgkmcnt(0)
	s_barrier
	ds_read_b128 v[176:179], v98 offset:16384
	ds_read_b128 v[180:183], v98 offset:20480
	ds_read_b128 v[184:187], v222 offset:49152
	ds_read_b128 v[188:191], v222 offset:57344
	v_mfma_f32_32x32x16_bf16 v[34:49], v[206:209], v[214:217], v[34:49]
	v_mfma_f32_32x32x16_bf16 v[50:65], v[206:209], v[218:221], v[50:65]
	v_mfma_f32_32x32x16_bf16 v[2:17], v[210:213], v[214:217], v[2:17]
	v_mfma_f32_32x32x16_bf16 v[18:33], v[210:213], v[218:221], v[18:33]
	ds_read_b128 v[206:209], v99 offset:16384
	ds_read_b128 v[210:213], v99 offset:20480
	ds_read_b128 v[214:217], v223 offset:49152
	ds_read_b128 v[218:221], v223 offset:57344
	s_waitcnt lgkmcnt(4)
	v_mfma_f32_32x32x16_bf16 v[34:49], v[176:179], v[184:187], v[34:49]
	v_mfma_f32_32x32x16_bf16 v[50:65], v[176:179], v[188:191], v[50:65]
	v_mfma_f32_32x32x16_bf16 v[2:17], v[180:183], v[184:187], v[2:17]
	v_mfma_f32_32x32x16_bf16 v[18:33], v[180:183], v[188:191], v[18:33]
	ds_read_b128 v[176:179], v100 offset:16384
	ds_read_b128 v[180:183], v100 offset:20480
	ds_read_b128 v[184:187], v224 offset:49152
	ds_read_b128 v[188:191], v224 offset:57344
	s_waitcnt lgkmcnt(4)
	v_mfma_f32_32x32x16_bf16 v[34:49], v[206:209], v[214:217], v[34:49]
	v_mfma_f32_32x32x16_bf16 v[50:65], v[206:209], v[218:221], v[50:65]
	v_mfma_f32_32x32x16_bf16 v[2:17], v[210:213], v[214:217], v[2:17]
	v_mfma_f32_32x32x16_bf16 v[18:33], v[210:213], v[218:221], v[18:33]
	ds_read_b128 v[206:209], v101 offset:16384
	ds_read_b128 v[210:213], v101 offset:20480
	ds_read_b128 v[214:217], v225 offset:49152
	ds_read_b128 v[218:221], v225 offset:57344
	s_waitcnt lgkmcnt(4)
	v_mfma_f32_32x32x16_bf16 v[34:49], v[176:179], v[184:187], v[34:49]
	v_mfma_f32_32x32x16_bf16 v[50:65], v[176:179], v[188:191], v[50:65]
	v_mfma_f32_32x32x16_bf16 v[2:17], v[180:183], v[184:187], v[2:17]
	v_mfma_f32_32x32x16_bf16 v[18:33], v[180:183], v[188:191], v[18:33]
	s_waitcnt vmcnt(0) lgkmcnt(0)
	s_barrier
	v_mfma_f32_32x32x16_bf16 v[34:49], v[206:209], v[214:217], v[34:49]
	v_mfma_f32_32x32x16_bf16 v[50:65], v[206:209], v[218:221], v[50:65]
	v_mfma_f32_32x32x16_bf16 v[2:17], v[210:213], v[214:217], v[2:17]
	v_mfma_f32_32x32x16_bf16 v[18:33], v[210:213], v[218:221], v[18:33]
	s_nop 15
	v_mul_f32_e32 v79, 0xbfb8aa3b, v34
	v_exp_f32_e32 v79, v79
	v_or_b32_e32 v76, s4, v88
	v_ashrrev_i32_e32 v77, 31, v76
	v_lshl_add_u64 v[76:77], v[76:77], 1, s[8:9]
	v_add_f32_e32 v79, 1.0, v79
	v_add_u32_e32 v78, s1, v97
	v_div_scale_f32 v80, s[4:5], v79, v79, v34
	v_rcp_f32_e32 v81, v80
	s_nop 0
	v_fma_f32 v82, -v80, v81, 1.0
	v_fmac_f32_e32 v81, v82, v81
	v_div_scale_f32 v82, vcc, v34, v79, v34
	v_mul_f32_e32 v83, v82, v81
	v_fma_f32 v84, -v80, v83, v82
	v_fmac_f32_e32 v83, v84, v81
	v_fma_f32 v80, -v80, v83, v82
	v_div_fmas_f32 v80, v80, v81, v83
	v_div_fixup_f32 v34, v80, v79, v34
	v_mul_f32_e32 v34, v50, v34
	v_bfe_u32 v50, v34, 16, 1
	v_add3_u32 v34, v34, v50, s26
	v_mul_f32_e32 v50, 0xbfb8aa3b, v35
	v_exp_f32_e32 v50, v50
	v_mad_i64_i32 v[80:81], s[4:5], v78, s50, v[76:77]
	global_store_short_d16_hi v[80:81], v34, off
	v_add_f32_e32 v50, 1.0, v50
	v_div_scale_f32 v79, s[4:5], v50, v50, v35
	v_rcp_f32_e32 v80, v79
	v_or_b32_e32 v34, 1, v78
	v_fma_f32 v81, -v79, v80, 1.0
	v_fmac_f32_e32 v80, v81, v80
	v_div_scale_f32 v81, vcc, v35, v50, v35
	v_mul_f32_e32 v82, v81, v80
	v_fma_f32 v83, -v79, v82, v81
	v_fmac_f32_e32 v82, v83, v80
	v_fma_f32 v79, -v79, v82, v81
	v_div_fmas_f32 v79, v79, v80, v82
	v_div_fixup_f32 v35, v79, v50, v35
	v_mul_f32_e32 v35, v51, v35
	v_bfe_u32 v50, v35, 16, 1
	v_add3_u32 v50, v35, v50, s26
	v_mad_i64_i32 v[34:35], s[4:5], v34, s50, v[76:77]
	global_store_short_d16_hi v[34:35], v50, off
	v_mul_f32_e32 v35, 0xbfb8aa3b, v36
	v_exp_f32_e32 v35, v35
	v_or_b32_e32 v34, 2, v78
	v_add_f32_e32 v35, 1.0, v35
	v_div_scale_f32 v50, s[4:5], v35, v35, v36
	v_rcp_f32_e32 v51, v50
	s_nop 0
	v_fma_f32 v79, -v50, v51, 1.0
	v_fmac_f32_e32 v51, v79, v51
	v_div_scale_f32 v79, vcc, v36, v35, v36
	v_mul_f32_e32 v80, v79, v51
	v_fma_f32 v81, -v50, v80, v79
	v_fmac_f32_e32 v80, v81, v51
	v_fma_f32 v50, -v50, v80, v79
	v_div_fmas_f32 v50, v50, v51, v80
	v_div_fixup_f32 v35, v50, v35, v36
	v_mul_f32_e32 v35, v52, v35
	v_bfe_u32 v36, v35, 16, 1
	v_add3_u32 v36, v35, v36, s26
	v_mad_i64_i32 v[34:35], s[4:5], v34, s50, v[76:77]
	global_store_short_d16_hi v[34:35], v36, off
	v_mul_f32_e32 v35, 0xbfb8aa3b, v37
	v_exp_f32_e32 v35, v35
	v_or_b32_e32 v34, 3, v78
	v_add_f32_e32 v35, 1.0, v35
	v_div_scale_f32 v36, s[4:5], v35, v35, v37
	v_rcp_f32_e32 v50, v36
	s_nop 0
	v_fma_f32 v51, -v36, v50, 1.0
	v_fmac_f32_e32 v50, v51, v50
	v_div_scale_f32 v51, vcc, v37, v35, v37
	v_mul_f32_e32 v52, v51, v50
	v_fma_f32 v79, -v36, v52, v51
	v_fmac_f32_e32 v52, v79, v50
	v_fma_f32 v36, -v36, v52, v51
	v_div_fmas_f32 v36, v36, v50, v52
	v_div_fixup_f32 v35, v36, v35, v37
	v_mul_f32_e32 v35, v53, v35
	v_bfe_u32 v36, v35, 16, 1
	v_add3_u32 v36, v35, v36, s26
	v_mad_i64_i32 v[34:35], s[4:5], v34, s50, v[76:77]
	global_store_short_d16_hi v[34:35], v36, off
	v_mul_f32_e32 v35, 0xbfb8aa3b, v38
	v_exp_f32_e32 v35, v35
	v_or_b32_e32 v34, 8, v78
	v_add_f32_e32 v35, 1.0, v35
	v_div_scale_f32 v36, s[4:5], v35, v35, v38
	v_rcp_f32_e32 v37, v36
	s_nop 0
	v_fma_f32 v50, -v36, v37, 1.0
	v_fmac_f32_e32 v37, v50, v37
	v_div_scale_f32 v50, vcc, v38, v35, v38
	v_mul_f32_e32 v51, v50, v37
	v_fma_f32 v52, -v36, v51, v50
	v_fmac_f32_e32 v51, v52, v37
	v_fma_f32 v36, -v36, v51, v50
	v_div_fmas_f32 v36, v36, v37, v51
	v_div_fixup_f32 v35, v36, v35, v38
	v_mul_f32_e32 v35, v54, v35
	v_bfe_u32 v36, v35, 16, 1
	v_add3_u32 v36, v35, v36, s26
	v_mad_i64_i32 v[34:35], s[4:5], v34, s50, v[76:77]
	global_store_short_d16_hi v[34:35], v36, off
	v_mul_f32_e32 v35, 0xbfb8aa3b, v39
	v_exp_f32_e32 v35, v35
	v_or_b32_e32 v34, 9, v78
	v_add_f32_e32 v35, 1.0, v35
	v_div_scale_f32 v36, s[4:5], v35, v35, v39
	v_rcp_f32_e32 v37, v36
	s_nop 0
	v_fma_f32 v38, -v36, v37, 1.0
	v_fmac_f32_e32 v37, v38, v37
	v_div_scale_f32 v38, vcc, v39, v35, v39
	v_mul_f32_e32 v50, v38, v37
	v_fma_f32 v51, -v36, v50, v38
	v_fmac_f32_e32 v50, v51, v37
	v_fma_f32 v36, -v36, v50, v38
	v_div_fmas_f32 v36, v36, v37, v50
	v_div_fixup_f32 v35, v36, v35, v39
	v_mul_f32_e32 v35, v55, v35
	v_bfe_u32 v36, v35, 16, 1
	v_add3_u32 v36, v35, v36, s26
	v_mad_i64_i32 v[34:35], s[4:5], v34, s50, v[76:77]
	global_store_short_d16_hi v[34:35], v36, off
	v_mul_f32_e32 v35, 0xbfb8aa3b, v40
	v_exp_f32_e32 v35, v35
	v_or_b32_e32 v34, 10, v78
	v_add_f32_e32 v35, 1.0, v35
	v_div_scale_f32 v36, s[4:5], v35, v35, v40
	v_rcp_f32_e32 v37, v36
	s_nop 0
	v_fma_f32 v38, -v36, v37, 1.0
	v_fmac_f32_e32 v37, v38, v37
	v_div_scale_f32 v38, vcc, v40, v35, v40
	v_mul_f32_e32 v39, v38, v37
	v_fma_f32 v50, -v36, v39, v38
	v_fmac_f32_e32 v39, v50, v37
	v_fma_f32 v36, -v36, v39, v38
	v_div_fmas_f32 v36, v36, v37, v39
	v_div_fixup_f32 v35, v36, v35, v40
	v_mul_f32_e32 v35, v56, v35
	v_bfe_u32 v36, v35, 16, 1
	v_add3_u32 v36, v35, v36, s26
	v_mad_i64_i32 v[34:35], s[4:5], v34, s50, v[76:77]
	global_store_short_d16_hi v[34:35], v36, off
	v_mul_f32_e32 v35, 0xbfb8aa3b, v41
	v_exp_f32_e32 v35, v35
	v_or_b32_e32 v34, 11, v78
	v_add_f32_e32 v35, 1.0, v35
	v_div_scale_f32 v36, s[4:5], v35, v35, v41
	v_rcp_f32_e32 v37, v36
	s_nop 0
	v_fma_f32 v38, -v36, v37, 1.0
	v_fmac_f32_e32 v37, v38, v37
	v_div_scale_f32 v38, vcc, v41, v35, v41
	v_mul_f32_e32 v39, v38, v37
	v_fma_f32 v40, -v36, v39, v38
	v_fmac_f32_e32 v39, v40, v37
	v_fma_f32 v36, -v36, v39, v38
	v_div_fmas_f32 v36, v36, v37, v39
	v_div_fixup_f32 v35, v36, v35, v41
	v_mul_f32_e32 v35, v57, v35
	v_bfe_u32 v36, v35, 16, 1
	v_add3_u32 v36, v35, v36, s26
	v_mad_i64_i32 v[34:35], s[4:5], v34, s50, v[76:77]
	global_store_short_d16_hi v[34:35], v36, off
	v_mul_f32_e32 v35, 0xbfb8aa3b, v42
	v_exp_f32_e32 v35, v35
	v_or_b32_e32 v34, 16, v78
	v_add_f32_e32 v35, 1.0, v35
	v_div_scale_f32 v36, s[4:5], v35, v35, v42
	v_rcp_f32_e32 v37, v36
	s_nop 0
	v_fma_f32 v38, -v36, v37, 1.0
	v_fmac_f32_e32 v37, v38, v37
	v_div_scale_f32 v38, vcc, v42, v35, v42
	v_mul_f32_e32 v39, v38, v37
	v_fma_f32 v40, -v36, v39, v38
	v_fmac_f32_e32 v39, v40, v37
	v_fma_f32 v36, -v36, v39, v38
	v_div_fmas_f32 v36, v36, v37, v39
	v_div_fixup_f32 v35, v36, v35, v42
	v_mul_f32_e32 v35, v58, v35
	v_bfe_u32 v36, v35, 16, 1
	v_add3_u32 v36, v35, v36, s26
	v_mad_i64_i32 v[34:35], s[4:5], v34, s50, v[76:77]
	global_store_short_d16_hi v[34:35], v36, off
	v_mul_f32_e32 v35, 0xbfb8aa3b, v43
	v_exp_f32_e32 v35, v35
	v_or_b32_e32 v34, 17, v78
	v_add_f32_e32 v35, 1.0, v35
	v_div_scale_f32 v36, s[4:5], v35, v35, v43
	v_rcp_f32_e32 v37, v36
	s_nop 0
	v_fma_f32 v38, -v36, v37, 1.0
	v_fmac_f32_e32 v37, v38, v37
	v_div_scale_f32 v38, vcc, v43, v35, v43
	v_mul_f32_e32 v39, v38, v37
	v_fma_f32 v40, -v36, v39, v38
	v_fmac_f32_e32 v39, v40, v37
	v_fma_f32 v36, -v36, v39, v38
	v_div_fmas_f32 v36, v36, v37, v39
	v_div_fixup_f32 v35, v36, v35, v43
	v_mul_f32_e32 v35, v59, v35
	v_bfe_u32 v36, v35, 16, 1
	v_add3_u32 v36, v35, v36, s26
	v_mad_i64_i32 v[34:35], s[4:5], v34, s50, v[76:77]
	global_store_short_d16_hi v[34:35], v36, off
	v_mul_f32_e32 v35, 0xbfb8aa3b, v44
	v_exp_f32_e32 v35, v35
	v_or_b32_e32 v34, 18, v78
	v_add_f32_e32 v35, 1.0, v35
	v_div_scale_f32 v36, s[4:5], v35, v35, v44
	v_rcp_f32_e32 v37, v36
	s_nop 0
	v_fma_f32 v38, -v36, v37, 1.0
	v_fmac_f32_e32 v37, v38, v37
	v_div_scale_f32 v38, vcc, v44, v35, v44
	v_mul_f32_e32 v39, v38, v37
	v_fma_f32 v40, -v36, v39, v38
	v_fmac_f32_e32 v39, v40, v37
	v_fma_f32 v36, -v36, v39, v38
	v_div_fmas_f32 v36, v36, v37, v39
	v_div_fixup_f32 v35, v36, v35, v44
	v_mul_f32_e32 v35, v60, v35
	v_bfe_u32 v36, v35, 16, 1
	v_add3_u32 v36, v35, v36, s26
	v_mad_i64_i32 v[34:35], s[4:5], v34, s50, v[76:77]
	global_store_short_d16_hi v[34:35], v36, off
	v_mul_f32_e32 v35, 0xbfb8aa3b, v45
	v_exp_f32_e32 v35, v35
	v_or_b32_e32 v34, 19, v78
	v_add_f32_e32 v35, 1.0, v35
	v_div_scale_f32 v36, s[4:5], v35, v35, v45
	v_rcp_f32_e32 v37, v36
	s_nop 0
	v_fma_f32 v38, -v36, v37, 1.0
	v_fmac_f32_e32 v37, v38, v37
	v_div_scale_f32 v38, vcc, v45, v35, v45
	v_mul_f32_e32 v39, v38, v37
	v_fma_f32 v40, -v36, v39, v38
	v_fmac_f32_e32 v39, v40, v37
	v_fma_f32 v36, -v36, v39, v38
	v_div_fmas_f32 v36, v36, v37, v39
	v_div_fixup_f32 v35, v36, v35, v45
	v_mul_f32_e32 v35, v61, v35
	v_bfe_u32 v36, v35, 16, 1
	v_add3_u32 v36, v35, v36, s26
	v_mad_i64_i32 v[34:35], s[4:5], v34, s50, v[76:77]
	global_store_short_d16_hi v[34:35], v36, off
	v_mul_f32_e32 v35, 0xbfb8aa3b, v46
	v_exp_f32_e32 v35, v35
	v_or_b32_e32 v34, 24, v78
	v_add_f32_e32 v35, 1.0, v35
	v_div_scale_f32 v36, s[4:5], v35, v35, v46
	v_rcp_f32_e32 v37, v36
	s_nop 0
	v_fma_f32 v38, -v36, v37, 1.0
	v_fmac_f32_e32 v37, v38, v37
	v_div_scale_f32 v38, vcc, v46, v35, v46
	v_mul_f32_e32 v39, v38, v37
	v_fma_f32 v40, -v36, v39, v38
	v_fmac_f32_e32 v39, v40, v37
	v_fma_f32 v36, -v36, v39, v38
	v_div_fmas_f32 v36, v36, v37, v39
	v_div_fixup_f32 v35, v36, v35, v46
	v_mul_f32_e32 v35, v62, v35
	v_bfe_u32 v36, v35, 16, 1
	v_add3_u32 v36, v35, v36, s26
	v_mad_i64_i32 v[34:35], s[4:5], v34, s50, v[76:77]
	global_store_short_d16_hi v[34:35], v36, off
	v_mul_f32_e32 v35, 0xbfb8aa3b, v47
	v_exp_f32_e32 v35, v35
	v_or_b32_e32 v34, 25, v78
	v_add_f32_e32 v35, 1.0, v35
	v_div_scale_f32 v36, s[4:5], v35, v35, v47
	v_rcp_f32_e32 v37, v36
	s_nop 0
	v_fma_f32 v38, -v36, v37, 1.0
	v_fmac_f32_e32 v37, v38, v37
	v_div_scale_f32 v38, vcc, v47, v35, v47
	v_mul_f32_e32 v39, v38, v37
	v_fma_f32 v40, -v36, v39, v38
	v_fmac_f32_e32 v39, v40, v37
	v_fma_f32 v36, -v36, v39, v38
	v_div_fmas_f32 v36, v36, v37, v39
	v_div_fixup_f32 v35, v36, v35, v47
	v_mul_f32_e32 v35, v63, v35
	v_bfe_u32 v36, v35, 16, 1
	v_add3_u32 v36, v35, v36, s26
	v_mad_i64_i32 v[34:35], s[4:5], v34, s50, v[76:77]
	global_store_short_d16_hi v[34:35], v36, off
	v_mul_f32_e32 v35, 0xbfb8aa3b, v48
	v_exp_f32_e32 v35, v35
	v_or_b32_e32 v34, 26, v78
	v_add_f32_e32 v35, 1.0, v35
	v_div_scale_f32 v36, s[4:5], v35, v35, v48
	v_rcp_f32_e32 v37, v36
	s_nop 0
	v_fma_f32 v38, -v36, v37, 1.0
	v_fmac_f32_e32 v37, v38, v37
	v_div_scale_f32 v38, vcc, v48, v35, v48
	v_mul_f32_e32 v39, v38, v37
	v_fma_f32 v40, -v36, v39, v38
	v_fmac_f32_e32 v39, v40, v37
	v_fma_f32 v36, -v36, v39, v38
	v_div_fmas_f32 v36, v36, v37, v39
	v_div_fixup_f32 v35, v36, v35, v48
	v_mul_f32_e32 v35, v64, v35
	v_bfe_u32 v36, v35, 16, 1
	v_add3_u32 v36, v35, v36, s26
	v_mad_i64_i32 v[34:35], s[4:5], v34, s50, v[76:77]
	global_store_short_d16_hi v[34:35], v36, off
	v_mul_f32_e32 v35, 0xbfb8aa3b, v49
	v_exp_f32_e32 v35, v35
	v_or_b32_e32 v34, 27, v78
	v_add_f32_e32 v35, 1.0, v35
	v_div_scale_f32 v36, s[4:5], v35, v35, v49
	v_rcp_f32_e32 v37, v36
	s_nop 0
	v_fma_f32 v38, -v36, v37, 1.0
	v_fmac_f32_e32 v37, v38, v37
	v_div_scale_f32 v38, vcc, v49, v35, v49
	v_mul_f32_e32 v39, v38, v37
	v_fma_f32 v40, -v36, v39, v38
	v_fmac_f32_e32 v39, v40, v37
	v_fma_f32 v36, -v36, v39, v38
	v_div_fmas_f32 v36, v36, v37, v39
	v_div_fixup_f32 v35, v36, v35, v49
	v_mul_f32_e32 v35, v65, v35
	v_bfe_u32 v36, v35, 16, 1
	v_add3_u32 v36, v35, v36, s26
	v_mad_i64_i32 v[34:35], s[4:5], v34, s50, v[76:77]
	global_store_short_d16_hi v[34:35], v36, off
	v_mul_f32_e32 v35, 0xbfb8aa3b, v2
	v_exp_f32_e32 v35, v35
	v_or_b32_e32 v34, 32, v78
	v_add_f32_e32 v35, 1.0, v35
	v_div_scale_f32 v36, s[4:5], v35, v35, v2
	v_rcp_f32_e32 v37, v36
	s_nop 0
	v_fma_f32 v38, -v36, v37, 1.0
	v_fmac_f32_e32 v37, v38, v37
	v_div_scale_f32 v38, vcc, v2, v35, v2
	v_mul_f32_e32 v39, v38, v37
	v_fma_f32 v40, -v36, v39, v38
	v_fmac_f32_e32 v39, v40, v37
	v_fma_f32 v36, -v36, v39, v38
	v_div_fmas_f32 v36, v36, v37, v39
	v_div_fixup_f32 v2, v36, v35, v2
	v_mul_f32_e32 v2, v18, v2
	v_bfe_u32 v18, v2, 16, 1
	v_add3_u32 v2, v2, v18, s26
	v_mul_f32_e32 v18, 0xbfb8aa3b, v3
	v_exp_f32_e32 v18, v18
	v_mad_i64_i32 v[34:35], s[4:5], v34, s50, v[76:77]
	global_store_short_d16_hi v[34:35], v2, off
	v_add_f32_e32 v18, 1.0, v18
	v_div_scale_f32 v34, s[4:5], v18, v18, v3
	v_rcp_f32_e32 v35, v34
	v_or_b32_e32 v2, 33, v78
	v_fma_f32 v36, -v34, v35, 1.0
	v_fmac_f32_e32 v35, v36, v35
	v_div_scale_f32 v36, vcc, v3, v18, v3
	v_mul_f32_e32 v37, v36, v35
	v_fma_f32 v38, -v34, v37, v36
	v_fmac_f32_e32 v37, v38, v35
	v_fma_f32 v34, -v34, v37, v36
	v_div_fmas_f32 v34, v34, v35, v37
	v_div_fixup_f32 v3, v34, v18, v3
	v_mul_f32_e32 v3, v19, v3
	v_bfe_u32 v18, v3, 16, 1
	v_add3_u32 v18, v3, v18, s26
	v_mad_i64_i32 v[2:3], s[4:5], v2, s50, v[76:77]
	global_store_short_d16_hi v[2:3], v18, off
	v_mul_f32_e32 v3, 0xbfb8aa3b, v4
	v_exp_f32_e32 v3, v3
	v_or_b32_e32 v2, 34, v78
	v_add_f32_e32 v3, 1.0, v3
	v_div_scale_f32 v18, s[4:5], v3, v3, v4
	v_rcp_f32_e32 v19, v18
	s_nop 0
	v_fma_f32 v34, -v18, v19, 1.0
	v_fmac_f32_e32 v19, v34, v19
	v_div_scale_f32 v34, vcc, v4, v3, v4
	v_mul_f32_e32 v35, v34, v19
	v_fma_f32 v36, -v18, v35, v34
	v_fmac_f32_e32 v35, v36, v19
	v_fma_f32 v18, -v18, v35, v34
	v_div_fmas_f32 v18, v18, v19, v35
	v_div_fixup_f32 v3, v18, v3, v4
	v_mul_f32_e32 v3, v20, v3
	v_bfe_u32 v4, v3, 16, 1
	v_add3_u32 v4, v3, v4, s26
	v_mad_i64_i32 v[2:3], s[4:5], v2, s50, v[76:77]
	global_store_short_d16_hi v[2:3], v4, off
	v_mul_f32_e32 v3, 0xbfb8aa3b, v5
	v_exp_f32_e32 v3, v3
	v_or_b32_e32 v2, 35, v78
	v_add_f32_e32 v3, 1.0, v3
	v_div_scale_f32 v4, s[4:5], v3, v3, v5
	v_rcp_f32_e32 v18, v4
	s_nop 0
	v_fma_f32 v19, -v4, v18, 1.0
	v_fmac_f32_e32 v18, v19, v18
	v_div_scale_f32 v19, vcc, v5, v3, v5
	v_mul_f32_e32 v20, v19, v18
	v_fma_f32 v34, -v4, v20, v19
	v_fmac_f32_e32 v20, v34, v18
	v_fma_f32 v4, -v4, v20, v19
	v_div_fmas_f32 v4, v4, v18, v20
	v_div_fixup_f32 v3, v4, v3, v5
	v_mul_f32_e32 v3, v21, v3
	v_bfe_u32 v4, v3, 16, 1
	v_add3_u32 v4, v3, v4, s26
	v_mad_i64_i32 v[2:3], s[4:5], v2, s50, v[76:77]
	global_store_short_d16_hi v[2:3], v4, off
	v_mul_f32_e32 v3, 0xbfb8aa3b, v6
	v_exp_f32_e32 v3, v3
	v_or_b32_e32 v2, 40, v78
	v_add_f32_e32 v3, 1.0, v3
	v_div_scale_f32 v4, s[4:5], v3, v3, v6
	v_rcp_f32_e32 v5, v4
	s_nop 0
	v_fma_f32 v18, -v4, v5, 1.0
	v_fmac_f32_e32 v5, v18, v5
	v_div_scale_f32 v18, vcc, v6, v3, v6
	v_mul_f32_e32 v19, v18, v5
	v_fma_f32 v20, -v4, v19, v18
	v_fmac_f32_e32 v19, v20, v5
	v_fma_f32 v4, -v4, v19, v18
	v_div_fmas_f32 v4, v4, v5, v19
	v_div_fixup_f32 v3, v4, v3, v6
	v_mul_f32_e32 v3, v22, v3
	v_bfe_u32 v4, v3, 16, 1
	v_add3_u32 v4, v3, v4, s26
	v_mad_i64_i32 v[2:3], s[4:5], v2, s50, v[76:77]
	global_store_short_d16_hi v[2:3], v4, off
	v_mul_f32_e32 v3, 0xbfb8aa3b, v7
	v_exp_f32_e32 v3, v3
	v_or_b32_e32 v2, 41, v78
	v_add_f32_e32 v3, 1.0, v3
	v_div_scale_f32 v4, s[4:5], v3, v3, v7
	v_rcp_f32_e32 v5, v4
	s_nop 0
	v_fma_f32 v6, -v4, v5, 1.0
	v_fmac_f32_e32 v5, v6, v5
	v_div_scale_f32 v6, vcc, v7, v3, v7
	v_mul_f32_e32 v18, v6, v5
	v_fma_f32 v19, -v4, v18, v6
	v_fmac_f32_e32 v18, v19, v5
	v_fma_f32 v4, -v4, v18, v6
	v_div_fmas_f32 v4, v4, v5, v18
	v_div_fixup_f32 v3, v4, v3, v7
	v_mul_f32_e32 v3, v23, v3
	v_bfe_u32 v4, v3, 16, 1
	v_add3_u32 v4, v3, v4, s26
	v_mad_i64_i32 v[2:3], s[4:5], v2, s50, v[76:77]
	global_store_short_d16_hi v[2:3], v4, off
	v_mul_f32_e32 v3, 0xbfb8aa3b, v8
	v_exp_f32_e32 v3, v3
	v_or_b32_e32 v2, 42, v78
	v_add_f32_e32 v3, 1.0, v3
	v_div_scale_f32 v4, s[4:5], v3, v3, v8
	v_rcp_f32_e32 v5, v4
	s_nop 0
	v_fma_f32 v6, -v4, v5, 1.0
	v_fmac_f32_e32 v5, v6, v5
	v_div_scale_f32 v6, vcc, v8, v3, v8
	v_mul_f32_e32 v7, v6, v5
	v_fma_f32 v18, -v4, v7, v6
	v_fmac_f32_e32 v7, v18, v5
	v_fma_f32 v4, -v4, v7, v6
	v_div_fmas_f32 v4, v4, v5, v7
	v_div_fixup_f32 v3, v4, v3, v8
	v_mul_f32_e32 v3, v24, v3
	v_bfe_u32 v4, v3, 16, 1
	v_add3_u32 v4, v3, v4, s26
	v_mad_i64_i32 v[2:3], s[4:5], v2, s50, v[76:77]
	global_store_short_d16_hi v[2:3], v4, off
	v_mul_f32_e32 v3, 0xbfb8aa3b, v9
	v_exp_f32_e32 v3, v3
	v_or_b32_e32 v2, 43, v78
	v_add_f32_e32 v3, 1.0, v3
	v_div_scale_f32 v4, s[4:5], v3, v3, v9
	v_rcp_f32_e32 v5, v4
	s_nop 0
	v_fma_f32 v6, -v4, v5, 1.0
	v_fmac_f32_e32 v5, v6, v5
	v_div_scale_f32 v6, vcc, v9, v3, v9
	v_mul_f32_e32 v7, v6, v5
	v_fma_f32 v8, -v4, v7, v6
	v_fmac_f32_e32 v7, v8, v5
	v_fma_f32 v4, -v4, v7, v6
	v_div_fmas_f32 v4, v4, v5, v7
	v_div_fixup_f32 v3, v4, v3, v9
	v_mul_f32_e32 v3, v25, v3
	v_bfe_u32 v4, v3, 16, 1
	v_add3_u32 v4, v3, v4, s26
	v_mad_i64_i32 v[2:3], s[4:5], v2, s50, v[76:77]
	global_store_short_d16_hi v[2:3], v4, off
	v_mul_f32_e32 v3, 0xbfb8aa3b, v10
	v_exp_f32_e32 v3, v3
	v_or_b32_e32 v2, 48, v78
	v_add_f32_e32 v3, 1.0, v3
	v_div_scale_f32 v4, s[4:5], v3, v3, v10
	v_rcp_f32_e32 v5, v4
	s_nop 0
	v_fma_f32 v6, -v4, v5, 1.0
	v_fmac_f32_e32 v5, v6, v5
	v_div_scale_f32 v6, vcc, v10, v3, v10
	v_mul_f32_e32 v7, v6, v5
	v_fma_f32 v8, -v4, v7, v6
	v_fmac_f32_e32 v7, v8, v5
	v_fma_f32 v4, -v4, v7, v6
	v_div_fmas_f32 v4, v4, v5, v7
	v_div_fixup_f32 v3, v4, v3, v10
	v_mul_f32_e32 v3, v26, v3
	v_bfe_u32 v4, v3, 16, 1
	v_add3_u32 v4, v3, v4, s26
	v_mad_i64_i32 v[2:3], s[4:5], v2, s50, v[76:77]
	global_store_short_d16_hi v[2:3], v4, off
	v_mul_f32_e32 v3, 0xbfb8aa3b, v11
	v_exp_f32_e32 v3, v3
	v_or_b32_e32 v2, 49, v78
	v_add_f32_e32 v3, 1.0, v3
	v_div_scale_f32 v4, s[4:5], v3, v3, v11
	v_rcp_f32_e32 v5, v4
	s_nop 0
	v_fma_f32 v6, -v4, v5, 1.0
	v_fmac_f32_e32 v5, v6, v5
	v_div_scale_f32 v6, vcc, v11, v3, v11
	v_mul_f32_e32 v7, v6, v5
	v_fma_f32 v8, -v4, v7, v6
	v_fmac_f32_e32 v7, v8, v5
	v_fma_f32 v4, -v4, v7, v6
	v_div_fmas_f32 v4, v4, v5, v7
	v_div_fixup_f32 v3, v4, v3, v11
	v_mul_f32_e32 v3, v27, v3
	v_bfe_u32 v4, v3, 16, 1
	v_add3_u32 v4, v3, v4, s26
	v_mad_i64_i32 v[2:3], s[4:5], v2, s50, v[76:77]
	global_store_short_d16_hi v[2:3], v4, off
	v_mul_f32_e32 v3, 0xbfb8aa3b, v12
	v_exp_f32_e32 v3, v3
	v_or_b32_e32 v2, 50, v78
	v_add_f32_e32 v3, 1.0, v3
	v_div_scale_f32 v4, s[4:5], v3, v3, v12
	v_rcp_f32_e32 v5, v4
	s_nop 0
	v_fma_f32 v6, -v4, v5, 1.0
	v_fmac_f32_e32 v5, v6, v5
	v_div_scale_f32 v6, vcc, v12, v3, v12
	v_mul_f32_e32 v7, v6, v5
	v_fma_f32 v8, -v4, v7, v6
	v_fmac_f32_e32 v7, v8, v5
	v_fma_f32 v4, -v4, v7, v6
	v_div_fmas_f32 v4, v4, v5, v7
	v_div_fixup_f32 v3, v4, v3, v12
	v_mul_f32_e32 v3, v28, v3
	v_bfe_u32 v4, v3, 16, 1
	v_add3_u32 v4, v3, v4, s26
	v_mad_i64_i32 v[2:3], s[4:5], v2, s50, v[76:77]
	global_store_short_d16_hi v[2:3], v4, off
	v_mul_f32_e32 v3, 0xbfb8aa3b, v13
	v_exp_f32_e32 v3, v3
	v_or_b32_e32 v2, 51, v78
	v_add_f32_e32 v3, 1.0, v3
	v_div_scale_f32 v4, s[4:5], v3, v3, v13
	v_rcp_f32_e32 v5, v4
	s_nop 0
	v_fma_f32 v6, -v4, v5, 1.0
	v_fmac_f32_e32 v5, v6, v5
	v_div_scale_f32 v6, vcc, v13, v3, v13
	v_mul_f32_e32 v7, v6, v5
	v_fma_f32 v8, -v4, v7, v6
	v_fmac_f32_e32 v7, v8, v5
	v_fma_f32 v4, -v4, v7, v6
	v_div_fmas_f32 v4, v4, v5, v7
	v_div_fixup_f32 v3, v4, v3, v13
	v_mul_f32_e32 v3, v29, v3
	v_bfe_u32 v4, v3, 16, 1
	v_add3_u32 v4, v3, v4, s26
	v_mad_i64_i32 v[2:3], s[4:5], v2, s50, v[76:77]
	global_store_short_d16_hi v[2:3], v4, off
	v_mul_f32_e32 v3, 0xbfb8aa3b, v14
	v_exp_f32_e32 v3, v3
	v_or_b32_e32 v2, 56, v78
	v_add_f32_e32 v3, 1.0, v3
	v_div_scale_f32 v4, s[4:5], v3, v3, v14
	v_rcp_f32_e32 v5, v4
	s_nop 0
	v_fma_f32 v6, -v4, v5, 1.0
	v_fmac_f32_e32 v5, v6, v5
	v_div_scale_f32 v6, vcc, v14, v3, v14
	v_mul_f32_e32 v7, v6, v5
	v_fma_f32 v8, -v4, v7, v6
	v_fmac_f32_e32 v7, v8, v5
	v_fma_f32 v4, -v4, v7, v6
	v_div_fmas_f32 v4, v4, v5, v7
	v_div_fixup_f32 v3, v4, v3, v14
	v_mul_f32_e32 v3, v30, v3
	v_bfe_u32 v4, v3, 16, 1
	v_add3_u32 v4, v3, v4, s26
	v_mad_i64_i32 v[2:3], s[4:5], v2, s50, v[76:77]
	global_store_short_d16_hi v[2:3], v4, off
	v_mul_f32_e32 v3, 0xbfb8aa3b, v15
	v_exp_f32_e32 v3, v3
	v_or_b32_e32 v2, 57, v78
	v_add_f32_e32 v3, 1.0, v3
	v_div_scale_f32 v4, s[4:5], v3, v3, v15
	v_rcp_f32_e32 v5, v4
	s_nop 0
	v_fma_f32 v6, -v4, v5, 1.0
	v_fmac_f32_e32 v5, v6, v5
	v_div_scale_f32 v6, vcc, v15, v3, v15
	v_mul_f32_e32 v7, v6, v5
	v_fma_f32 v8, -v4, v7, v6
	v_fmac_f32_e32 v7, v8, v5
	v_fma_f32 v4, -v4, v7, v6
	v_div_fmas_f32 v4, v4, v5, v7
	v_div_fixup_f32 v3, v4, v3, v15
	v_mul_f32_e32 v3, v31, v3
	v_bfe_u32 v4, v3, 16, 1
	v_add3_u32 v4, v3, v4, s26
	v_mad_i64_i32 v[2:3], s[4:5], v2, s50, v[76:77]
	global_store_short_d16_hi v[2:3], v4, off
	v_mul_f32_e32 v3, 0xbfb8aa3b, v16
	v_exp_f32_e32 v3, v3
	v_or_b32_e32 v2, 58, v78
	v_add_f32_e32 v3, 1.0, v3
	v_div_scale_f32 v4, s[4:5], v3, v3, v16
	v_rcp_f32_e32 v5, v4
	s_nop 0
	v_fma_f32 v6, -v4, v5, 1.0
	v_fmac_f32_e32 v5, v6, v5
	v_div_scale_f32 v6, vcc, v16, v3, v16
	v_mul_f32_e32 v7, v6, v5
	v_fma_f32 v8, -v4, v7, v6
	v_fmac_f32_e32 v7, v8, v5
	v_fma_f32 v4, -v4, v7, v6
	v_div_fmas_f32 v4, v4, v5, v7
	v_div_fixup_f32 v3, v4, v3, v16
	v_mul_f32_e32 v3, v32, v3
	v_bfe_u32 v4, v3, 16, 1
	v_add3_u32 v4, v3, v4, s26
	v_mad_i64_i32 v[2:3], s[4:5], v2, s50, v[76:77]
	global_store_short_d16_hi v[2:3], v4, off
	v_mul_f32_e32 v3, 0xbfb8aa3b, v17
	v_exp_f32_e32 v3, v3
	v_or_b32_e32 v2, 59, v78
	v_add_f32_e32 v3, 1.0, v3
	v_div_scale_f32 v4, s[4:5], v3, v3, v17
	v_rcp_f32_e32 v5, v4
	s_nop 0
	v_fma_f32 v6, -v4, v5, 1.0
	v_fmac_f32_e32 v5, v6, v5
	v_div_scale_f32 v6, vcc, v17, v3, v17
	v_mul_f32_e32 v7, v6, v5
	v_fma_f32 v8, -v4, v7, v6
	v_fmac_f32_e32 v7, v8, v5
	v_fma_f32 v4, -v4, v7, v6
	v_div_fmas_f32 v4, v4, v5, v7
	v_div_fixup_f32 v3, v4, v3, v17
	v_mul_f32_e32 v3, v33, v3
	v_bfe_u32 v4, v3, 16, 1
	v_add3_u32 v4, v3, v4, s26
	v_mad_i64_i32 v[2:3], s[4:5], v2, s50, v[76:77]
	global_store_short_d16_hi v[2:3], v4, off
	s_load_dword s1, s[48:49], 0x0
	s_waitcnt lgkmcnt(0)
	s_add_i32 s0, s1, s0
	s_cmpk_gt_i32 s0, 0xaff
	s_cbranch_scc0 .LBB0_77

.LBB0_315:
	s_lshl_b32 s10, s16, 3
	s_and_b32 s13, s16, 0x3ff
	s_and_b32 s25, s16, 1
	s_bfe_u32 s27, s16, 0x20001
	s_and_b32 s22, s10, 0x1fc0
	s_cmpk_gt_i32 s16, 0x3ff
	s_mov_b64 s[10:11], -1
	s_waitcnt vmcnt(63) expcnt(7) lgkmcnt(15)
	s_barrier
	s_cbranch_scc0 .LBB0_319
	s_cmp_eq_u32 s25, 0
	s_cselect_b64 s[10:11], -1, 0
	s_lshl_b32 s64, s25, 9
	v_readlane_b32 s66, v253, 30
	v_readlane_b32 s67, v253, 31
	s_add_u32 s64, s66, s64
	s_addc_u32 s65, s67, 0
	s_lshl_b32 s92, s27, 7
	v_cndmask_b32_e64 v4, v72, v54, s[10:11]
	s_add_u32 s64, s64, s92
	v_add_u32_e32 v4, s22, v4
	s_addc_u32 s65, s65, 0
	v_mov_b32_e32 v47, v131
	v_ashrrev_i32_e32 v5, 31, v4
	v_lshl_add_u64 v[2:3], s[64:65], 0, v[46:47]
	v_lshlrev_b64 v[6:7], 10, v[4:5]
	v_lshl_add_u64 v[6:7], v[2:3], 0, v[6:7]
	global_load_dword v210, v[6:7], off
	v_cndmask_b32_e64 v5, v74, v73, s[10:11]
	v_add_u32_e32 v6, s22, v5
	v_ashrrev_i32_e32 v7, 31, v6
	v_lshlrev_b64 v[8:9], 10, v[6:7]
	v_lshl_add_u64 v[8:9], v[2:3], 0, v[8:9]
	global_load_dword v211, v[8:9], off
	v_cndmask_b32_e64 v5, v76, v75, s[10:11]
	v_add_u32_e32 v8, s22, v5
	v_ashrrev_i32_e32 v9, 31, v8
	v_lshlrev_b64 v[12:13], 10, v[8:9]
	v_lshl_add_u64 v[12:13], v[2:3], 0, v[12:13]
	global_load_dword v212, v[12:13], off
	v_cndmask_b32_e64 v5, v78, v77, s[10:11]
	v_add_u32_e32 v50, s22, v5
	v_ashrrev_i32_e32 v51, 31, v50
	v_lshlrev_b64 v[14:15], 10, v[50:51]
	v_lshl_add_u64 v[14:15], v[2:3], 0, v[14:15]
	global_load_dword v213, v[14:15], off
	v_cndmask_b32_e64 v5, v80, v79, s[10:11]
	v_add_u32_e32 v52, s22, v5
	v_ashrrev_i32_e32 v53, 31, v52
	v_lshlrev_b64 v[14:15], 10, v[52:53]
	v_lshl_add_u64 v[14:15], v[2:3], 0, v[14:15]
	global_load_dword v214, v[14:15], off
	v_cndmask_b32_e64 v5, v82, v81, s[10:11]
	v_add_u32_e32 v194, s22, v5
	v_ashrrev_i32_e32 v195, 31, v194
	v_lshlrev_b64 v[16:17], 10, v[194:195]
	v_lshl_add_u64 v[16:17], v[2:3], 0, v[16:17]
	global_load_dword v215, v[16:17], off
	v_cndmask_b32_e64 v5, v84, v83, s[10:11]
	v_add_u32_e32 v206, s22, v5
	v_ashrrev_i32_e32 v207, 31, v206
	v_lshlrev_b64 v[16:17], 10, v[206:207]
	v_lshl_add_u64 v[16:17], v[2:3], 0, v[16:17]
	global_load_dword v216, v[16:17], off
	v_cndmask_b32_e64 v5, v86, v85, s[10:11]
	v_add_u32_e32 v208, s22, v5
	v_ashrrev_i32_e32 v209, 31, v208
	v_lshlrev_b64 v[192:193], 10, v[208:209]
	v_lshl_add_u64 v[2:3], v[2:3], 0, v[192:193]
	global_load_dword v217, v[2:3], off
	s_waitcnt vmcnt(7)
	v_add_f32_e32 v10, 0, v210
	s_waitcnt vmcnt(6)
	v_add_f32_e32 v11, v10, v211
	s_waitcnt vmcnt(5)
	v_add_f32_e32 v12, v11, v212
	s_waitcnt vmcnt(4)
	v_add_f32_e32 v13, v12, v213
	s_waitcnt vmcnt(3)
	v_add_f32_e32 v15, v13, v214
	s_waitcnt vmcnt(2)
	v_add_f32_e32 v14, v15, v215
	s_waitcnt vmcnt(1)
	v_add_f32_e32 v16, v14, v216
	s_waitcnt vmcnt(0)
	v_add_f32_e32 v17, v16, v217
	v_mov_b64_e32 v[2:3], s[8:9]
	v_mad_i64_i32 v[4:5], s[64:65], v4, s15, v[2:3]
	v_lshl_add_u64 v[4:5], v[4:5], 0, s[92:93]
	v_lshl_add_u64 v[4:5], v[4:5], 0, v[46:47]
	global_load_dword v193, v[4:5], off offset:3584
	v_mad_i64_i32 v[4:5], s[64:65], v6, s15, v[2:3]
	v_lshl_add_u64 v[4:5], v[4:5], 0, s[92:93]
	v_lshl_add_u64 v[4:5], v[4:5], 0, v[46:47]
	global_load_dword v191, v[4:5], off offset:3584
	v_mad_i64_i32 v[4:5], s[64:65], v8, s15, v[2:3]
	v_lshl_add_u64 v[4:5], v[4:5], 0, s[92:93]
	v_lshl_add_u64 v[4:5], v[4:5], 0, v[46:47]
	global_load_dword v192, v[4:5], off offset:3584
	v_mad_i64_i32 v[4:5], s[64:65], v50, s15, v[2:3]
	v_lshl_add_u64 v[4:5], v[4:5], 0, s[92:93]
	v_lshl_add_u64 v[4:5], v[4:5], 0, v[46:47]
	global_load_dword v53, v[4:5], off offset:3584
	v_mad_i64_i32 v[4:5], s[64:65], v52, s15, v[2:3]
	v_lshl_add_u64 v[4:5], v[4:5], 0, s[92:93]
	v_lshl_add_u64 v[4:5], v[4:5], 0, v[46:47]
	global_load_dword v51, v[4:5], off offset:3584
	v_mad_i64_i32 v[4:5], s[64:65], v194, s15, v[2:3]
	v_lshl_add_u64 v[4:5], v[4:5], 0, s[92:93]
	v_lshl_add_u64 v[4:5], v[4:5], 0, v[46:47]
	global_load_dword v52, v[4:5], off offset:3584
	v_mad_i64_i32 v[4:5], s[64:65], v206, s15, v[2:3]
	v_mad_i64_i32 v[2:3], s[64:65], v208, s15, v[2:3]
	v_lshl_add_u64 v[4:5], v[4:5], 0, s[92:93]
	v_lshl_add_u64 v[2:3], v[2:3], 0, s[92:93]
	v_lshl_add_u64 v[4:5], v[4:5], 0, v[46:47]
	v_lshl_add_u64 v[2:3], v[2:3], 0, v[46:47]
	global_load_dword v50, v[4:5], off offset:3584
	global_load_dword v47, v[2:3], off offset:3584
	v_add_u32_e32 v6, 0x2000, v56
	ds_write_b32 v55, v17 offset:8448
	s_waitcnt lgkmcnt(0)
	s_barrier
	ds_read2_b32 v[4:5], v6 offset0:64 offset1:96
	ds_read2_b32 v[2:3], v6 offset0:128 offset1:160
	ds_read2_b32 v[6:7], v6 offset0:192 offset1:224
	v_add_u32_e32 v8, 0x2400, v56
	ds_read2_b32 v[8:9], v8 offset1:32
	s_waitcnt lgkmcnt(3)
	v_add_f32_e32 v194, 0, v4
	v_add_f32_e32 v4, v194, v5
	s_waitcnt lgkmcnt(2)
	v_add_f32_e32 v4, v4, v2
	v_add_f32_e32 v4, v4, v3
	s_waitcnt lgkmcnt(1)
	v_add_f32_e32 v4, v4, v6
	v_add_f32_e32 v4, v4, v7
	s_waitcnt lgkmcnt(0)
	v_add_f32_e32 v4, v4, v8
	v_add_f32_e32 v4, v4, v9
	s_and_saveexec_b64 s[64:65], s[20:21]
	s_cbranch_execz .LBB0_318
	v_mul_f32_e32 v195, 0x3fb8aa3b, v4
	v_exp_f32_e32 v195, v195
	v_readlane_b32 s66, v253, 44
	v_lshl_or_b32 v206, s13, 5, v19
	v_mov_b32_e32 v207, v131
	v_readlane_b32 s67, v253, 45
	s_nop 1
	v_lshl_add_u64 v[206:207], v[206:207], 2, s[66:67]
	global_store_dword v[206:207], v195, off

.LBB0_491:
	s_lshl_b32 s1, s6, 1
	s_and_b32 s1, s1, 0xffffff80
	v_add_u32_e32 v6, s1, v80
	v_min_i32_e32 v4, 0xa2f, v6
	v_ashrrev_i32_e32 v5, 31, v4
	v_lshlrev_b64 v[4:5], 11, v[4:5]
	v_lshl_add_u64 v[70:71], v[68:69], 0, v[4:5]
	v_add_u32_e32 v4, 32, v6
	s_lshl_b32 s0, s6, 7
	v_min_i32_e32 v4, 0xa2f, v4
	s_and_b32 s0, s0, 0x1f80
	v_ashrrev_i32_e32 v5, 31, v4
	v_add_u32_e32 v2, s0, v80
	v_lshlrev_b64 v[4:5], 11, v[4:5]
	v_ashrrev_i32_e32 v3, 31, v2
	v_lshl_add_u64 v[72:73], v[68:69], 0, v[4:5]
	v_add_u32_e32 v4, 64, v6
	v_lshlrev_b64 v[2:3], 11, v[2:3]
	v_min_i32_e32 v4, 0xa2f, v4
	v_readfirstlane_b32 s22, v83
	v_add_u32_e32 v137, 0x8000, v83
	v_ashrrev_i32_e32 v5, 31, v4
	v_lshl_add_u64 v[78:79], v[66:67], 0, v[2:3]
	s_mov_b32 m0, s22
	v_readfirstlane_b32 s24, v137
	v_add_u32_e32 v138, 0x1000, v83
	v_lshlrev_b64 v[4:5], 11, v[4:5]
	global_load_lds_dwordx4 v[78:79], off
	s_mov_b32 m0, s24
	s_mov_b64 s[4:5], 0x10000
	v_readfirstlane_b32 s25, v138
	v_add_u32_e32 v139, 0x9000, v83
	v_lshl_add_u64 v[74:75], v[68:69], 0, v[4:5]
	v_add_u32_e32 v4, 0x60, v6
	global_load_lds_dwordx4 v[70:71], off
	v_lshl_add_u64 v[2:3], v[78:79], 0, s[4:5]
	s_mov_b32 m0, s25
	v_readfirstlane_b32 s27, v139
	v_add_u32_e32 v140, 0x2000, v83
	v_min_i32_e32 v4, 0xa2f, v4
	global_load_lds_dwordx4 v[2:3], off
	s_mov_b32 m0, s27
	s_mov_b64 s[4:5], 0x20000
	v_readfirstlane_b32 s36, v140
	v_add_u32_e32 v134, 0xa000, v83
	v_ashrrev_i32_e32 v5, 31, v4
	global_load_lds_dwordx4 v[72:73], off
	v_lshl_add_u64 v[2:3], v[78:79], 0, s[4:5]
	s_mov_b32 m0, s36
	v_readfirstlane_b32 s37, v134
	v_add_u32_e32 v136, 0x3000, v83
	v_lshlrev_b64 v[4:5], 11, v[4:5]
	global_load_lds_dwordx4 v[2:3], off
	s_mov_b32 m0, s37
	s_mov_b64 s[4:5], 0x30000
	v_readfirstlane_b32 s38, v136
	v_add_u32_e32 v135, 0xb000, v83
	v_lshl_add_u64 v[76:77], v[68:69], 0, v[4:5]
	global_load_lds_dwordx4 v[74:75], off
	v_lshl_add_u64 v[2:3], v[78:79], 0, s[4:5]
	s_mov_b32 m0, s38
	v_readfirstlane_b32 s39, v135
	v_add_u32_e32 v4, 0x4000, v83
	global_load_lds_dwordx4 v[2:3], off
	s_mov_b32 m0, s39
	v_readfirstlane_b32 s4, v4
	v_add_u32_e32 v4, 0xc000, v83
	global_load_lds_dwordx4 v[76:77], off
	v_lshl_add_u64 v[2:3], v[78:79], 0, s[98:99]
	s_mov_b32 m0, s4
	v_readfirstlane_b32 s5, v4
	v_add_u32_e32 v4, 0x5000, v83
	s_waitcnt vmcnt(0)
	s_waitcnt vmcnt(0) lgkmcnt(0)
	s_barrier
	v_mov_b32_e32 v2, 0
	v_mov_b32_e32 v3, 0
	v_mov_b32_e32 v4, 0
	v_mov_b32_e32 v5, 0
	v_mov_b32_e32 v6, 0
	v_mov_b32_e32 v7, 0
	v_mov_b32_e32 v8, 0
	v_mov_b32_e32 v9, 0
	v_mov_b32_e32 v10, 0
	v_mov_b32_e32 v11, 0
	v_mov_b32_e32 v12, 0
	v_mov_b32_e32 v13, 0
	v_mov_b32_e32 v14, 0
	v_mov_b32_e32 v15, 0
	v_mov_b32_e32 v16, 0
	v_mov_b32_e32 v17, 0
	v_mov_b32_e32 v18, 0
	v_mov_b32_e32 v19, 0
	v_mov_b32_e32 v20, 0
	v_mov_b32_e32 v21, 0
	v_mov_b32_e32 v22, 0
	v_mov_b32_e32 v23, 0
	v_mov_b32_e32 v24, 0
	v_mov_b32_e32 v25, 0
	v_mov_b32_e32 v26, 0
	v_mov_b32_e32 v27, 0
	v_mov_b32_e32 v28, 0
	v_mov_b32_e32 v29, 0
	v_mov_b32_e32 v30, 0
	v_mov_b32_e32 v31, 0
	v_mov_b32_e32 v32, 0
	v_mov_b32_e32 v33, 0
	v_mov_b32_e32 v34, 0
	v_mov_b32_e32 v35, 0
	v_mov_b32_e32 v36, 0
	v_mov_b32_e32 v37, 0
	v_mov_b32_e32 v38, 0
	v_mov_b32_e32 v39, 0
	v_mov_b32_e32 v40, 0
	v_mov_b32_e32 v41, 0
	v_mov_b32_e32 v42, 0
	v_mov_b32_e32 v43, 0
	v_mov_b32_e32 v44, 0
	v_mov_b32_e32 v45, 0
	v_mov_b32_e32 v46, 0
	v_mov_b32_e32 v47, 0
	v_mov_b32_e32 v48, 0
	v_mov_b32_e32 v49, 0
	v_mov_b32_e32 v50, 0
	v_mov_b32_e32 v51, 0
	v_mov_b32_e32 v52, 0
	v_mov_b32_e32 v53, 0
	v_mov_b32_e32 v54, 0
	v_mov_b32_e32 v55, 0
	v_mov_b32_e32 v56, 0
	v_mov_b32_e32 v57, 0
	v_mov_b32_e32 v58, 0
	v_mov_b32_e32 v59, 0
	v_mov_b32_e32 v60, 0
	v_mov_b32_e32 v61, 0
	v_mov_b32_e32 v62, 0
	v_mov_b32_e32 v63, 0
	v_mov_b32_e32 v64, 0
	v_mov_b32_e32 v65, 0
	v_lshl_add_u64 v[164:165], v[78:79], 0, s[98:99]
	s_mov_b64 s[10:11], 0x10080
	v_lshl_add_u64 v[166:167], v[78:79], 0, s[10:11]
	s_mov_b64 s[10:11], 0x20080
	v_lshl_add_u64 v[168:169], v[78:79], 0, s[10:11]
	s_mov_b64 s[10:11], 0x30080
	v_lshl_add_u64 v[170:171], v[78:79], 0, s[10:11]
	v_lshl_add_u64 v[172:173], v[70:71], 0, s[98:99]
	v_lshl_add_u64 v[174:175], v[72:73], 0, s[98:99]
	v_lshl_add_u64 v[176:177], v[74:75], 0, s[98:99]
	v_lshl_add_u64 v[178:179], v[76:77], 0, s[98:99]
	v_add_u32_e32 v222, v119, v85
	v_add_u32_e32 v223, v118, v85
	v_add_u32_e32 v224, v117, v85
	v_add_u32_e32 v225, v116, v85
	s_mov_b32 s24, 7
	ds_read_b128 v[180:183], v120
	ds_read_b128 v[184:187], v120 offset:4096
	ds_read_b128 v[188:191], v222 offset:32768
	ds_read_b128 v[192:195], v222 offset:40960
.Lg0_loop:
	ds_read_b128 v[206:209], v121
	ds_read_b128 v[210:213], v121 offset:4096
	ds_read_b128 v[214:217], v223 offset:32768
	ds_read_b128 v[218:221], v223 offset:40960
	s_waitcnt lgkmcnt(4)
	v_mfma_f32_32x32x16_bf16 v[50:65], v[180:183], v[188:191], v[50:65]
	s_add_u32 m0, s22, 0x4000
	s_nop 0
	global_load_lds_dwordx4 v[164:165], off
	v_lshl_add_u64 v[164:165], v[164:165], 0, s[98:99]
	v_mfma_f32_32x32x16_bf16 v[34:49], v[180:183], v[192:195], v[34:49]
	s_add_u32 m0, s22, 0xc000
	s_nop 0
	global_load_lds_dwordx4 v[172:173], off
	v_lshl_add_u64 v[172:173], v[172:173], 0, s[98:99]
	v_mfma_f32_32x32x16_bf16 v[18:33], v[184:187], v[188:191], v[18:33]
	s_add_u32 m0, s22, 0x5000
	s_nop 0
	global_load_lds_dwordx4 v[166:167], off
	v_lshl_add_u64 v[166:167], v[166:167], 0, s[98:99]
	v_mfma_f32_32x32x16_bf16 v[2:17], v[184:187], v[192:195], v[2:17]
	ds_read_b128 v[180:183], v122
	ds_read_b128 v[184:187], v122 offset:4096
	ds_read_b128 v[188:191], v224 offset:32768
	ds_read_b128 v[192:195], v224 offset:40960
	s_waitcnt lgkmcnt(4)
	v_mfma_f32_32x32x16_bf16 v[50:65], v[206:209], v[214:217], v[50:65]
	s_add_u32 m0, s22, 0xd000
	s_nop 0
	global_load_lds_dwordx4 v[174:175], off
	v_lshl_add_u64 v[174:175], v[174:175], 0, s[98:99]
	v_mfma_f32_32x32x16_bf16 v[34:49], v[206:209], v[218:221], v[34:49]
	s_add_u32 m0, s22, 0x6000
	s_nop 0
	global_load_lds_dwordx4 v[168:169], off
	v_lshl_add_u64 v[168:169], v[168:169], 0, s[98:99]
	v_mfma_f32_32x32x16_bf16 v[18:33], v[210:213], v[214:217], v[18:33]
	s_add_u32 m0, s22, 0xe000
	s_nop 0
	global_load_lds_dwordx4 v[176:177], off
	v_lshl_add_u64 v[176:177], v[176:177], 0, s[98:99]
	v_mfma_f32_32x32x16_bf16 v[2:17], v[210:213], v[218:221], v[2:17]
	ds_read_b128 v[206:209], v123
	ds_read_b128 v[210:213], v123 offset:4096
	ds_read_b128 v[214:217], v225 offset:32768
	ds_read_b128 v[218:221], v225 offset:40960
	s_waitcnt lgkmcnt(4)
	v_mfma_f32_32x32x16_bf16 v[50:65], v[180:183], v[188:191], v[50:65]
	s_add_u32 m0, s22, 0x7000
	s_nop 0
	global_load_lds_dwordx4 v[170:171], off
	v_lshl_add_u64 v[170:171], v[170:171], 0, s[98:99]
	v_mfma_f32_32x32x16_bf16 v[34:49], v[180:183], v[192:195], v[34:49]
	s_add_u32 m0, s22, 0xf000
	s_nop 0
	global_load_lds_dwordx4 v[178:179], off
	v_lshl_add_u64 v[178:179], v[178:179], 0, s[98:99]
	v_mfma_f32_32x32x16_bf16 v[18:33], v[184:187], v[188:191], v[18:33]
	v_mfma_f32_32x32x16_bf16 v[2:17], v[184:187], v[192:195], v[2:17]
	s_waitcnt vmcnt(0) lgkmcnt(0)
	s_barrier
	ds_read_b128 v[180:183], v120 offset:16384
	ds_read_b128 v[184:187], v120 offset:20480
	ds_read_b128 v[188:191], v222 offset:49152
	ds_read_b128 v[192:195], v222 offset:57344
	v_mfma_f32_32x32x16_bf16 v[50:65], v[206:209], v[214:217], v[50:65]
	v_mfma_f32_32x32x16_bf16 v[34:49], v[206:209], v[218:221], v[34:49]
	v_mfma_f32_32x32x16_bf16 v[18:33], v[210:213], v[214:217], v[18:33]
	v_mfma_f32_32x32x16_bf16 v[2:17], v[210:213], v[218:221], v[2:17]
	ds_read_b128 v[206:209], v121 offset:16384
	ds_read_b128 v[210:213], v121 offset:20480
	ds_read_b128 v[214:217], v223 offset:49152
	ds_read_b128 v[218:221], v223 offset:57344
	s_waitcnt lgkmcnt(4)
	v_mfma_f32_32x32x16_bf16 v[50:65], v[180:183], v[188:191], v[50:65]
	s_mov_b32 m0, s22
	s_nop 0
	global_load_lds_dwordx4 v[164:165], off
	v_lshl_add_u64 v[164:165], v[164:165], 0, s[98:99]
	v_mfma_f32_32x32x16_bf16 v[34:49], v[180:183], v[192:195], v[34:49]
	s_add_u32 m0, s22, 0x8000
	s_nop 0
	global_load_lds_dwordx4 v[172:173], off
	v_lshl_add_u64 v[172:173], v[172:173], 0, s[98:99]
	v_mfma_f32_32x32x16_bf16 v[18:33], v[184:187], v[188:191], v[18:33]
	s_add_u32 m0, s22, 0x1000
	s_nop 0
	global_load_lds_dwordx4 v[166:167], off
	v_lshl_add_u64 v[166:167], v[166:167], 0, s[98:99]
	v_mfma_f32_32x32x16_bf16 v[2:17], v[184:187], v[192:195], v[2:17]
	ds_read_b128 v[180:183], v122 offset:16384
	ds_read_b128 v[184:187], v122 offset:20480
	ds_read_b128 v[188:191], v224 offset:49152
	ds_read_b128 v[192:195], v224 offset:57344
	s_waitcnt lgkmcnt(4)
	v_mfma_f32_32x32x16_bf16 v[50:65], v[206:209], v[214:217], v[50:65]
	s_add_u32 m0, s22, 0x9000
	s_nop 0
	global_load_lds_dwordx4 v[174:175], off
	v_lshl_add_u64 v[174:175], v[174:175], 0, s[98:99]
	v_mfma_f32_32x32x16_bf16 v[34:49], v[206:209], v[218:221], v[34:49]
	s_add_u32 m0, s22, 0x2000
	s_nop 0
	global_load_lds_dwordx4 v[168:169], off
	v_lshl_add_u64 v[168:169], v[168:169], 0, s[98:99]
	v_mfma_f32_32x32x16_bf16 v[18:33], v[210:213], v[214:217], v[18:33]
	s_add_u32 m0, s22, 0xa000
	s_nop 0
	global_load_lds_dwordx4 v[176:177], off
	v_lshl_add_u64 v[176:177], v[176:177], 0, s[98:99]
	v_mfma_f32_32x32x16_bf16 v[2:17], v[210:213], v[218:221], v[2:17]
	ds_read_b128 v[206:209], v123 offset:16384
	ds_read_b128 v[210:213], v123 offset:20480
	ds_read_b128 v[214:217], v225 offset:49152
	ds_read_b128 v[218:221], v225 offset:57344
	s_waitcnt lgkmcnt(4)
	v_mfma_f32_32x32x16_bf16 v[50:65], v[180:183], v[188:191], v[50:65]
	s_add_u32 m0, s22, 0x3000
	s_nop 0
	global_load_lds_dwordx4 v[170:171], off
	v_lshl_add_u64 v[170:171], v[170:171], 0, s[98:99]
	v_mfma_f32_32x32x16_bf16 v[34:49], v[180:183], v[192:195], v[34:49]
	s_add_u32 m0, s22, 0xb000
	s_nop 0
	global_load_lds_dwordx4 v[178:179], off
	v_lshl_add_u64 v[178:179], v[178:179], 0, s[98:99]
	v_mfma_f32_32x32x16_bf16 v[18:33], v[184:187], v[188:191], v[18:33]
	v_mfma_f32_32x32x16_bf16 v[2:17], v[184:187], v[192:195], v[2:17]
	s_waitcnt vmcnt(0) lgkmcnt(0)
	s_barrier
	ds_read_b128 v[180:183], v120
	ds_read_b128 v[184:187], v120 offset:4096
	ds_read_b128 v[188:191], v222 offset:32768
	ds_read_b128 v[192:195], v222 offset:40960
	v_mfma_f32_32x32x16_bf16 v[50:65], v[206:209], v[214:217], v[50:65]
	v_mfma_f32_32x32x16_bf16 v[34:49], v[206:209], v[218:221], v[34:49]
	v_mfma_f32_32x32x16_bf16 v[18:33], v[210:213], v[214:217], v[18:33]
	v_mfma_f32_32x32x16_bf16 v[2:17], v[210:213], v[218:221], v[2:17]
	s_sub_u32 s24, s24, 1
	s_cmp_lg_u32 s24, 0
	s_cbranch_scc1 .Lg0_loop
	ds_read_b128 v[206:209], v121
	ds_read_b128 v[210:213], v121 offset:4096
	ds_read_b128 v[214:217], v223 offset:32768
	ds_read_b128 v[218:221], v223 offset:40960
	s_waitcnt lgkmcnt(4)
	v_mfma_f32_32x32x16_bf16 v[50:65], v[180:183], v[188:191], v[50:65]
	s_add_u32 m0, s22, 0x4000
	s_nop 0
	global_load_lds_dwordx4 v[164:165], off
	v_lshl_add_u64 v[164:165], v[164:165], 0, s[98:99]
	v_mfma_f32_32x32x16_bf16 v[34:49], v[180:183], v[192:195], v[34:49]
	s_add_u32 m0, s22, 0xc000
	s_nop 0
	global_load_lds_dwordx4 v[172:173], off
	v_lshl_add_u64 v[172:173], v[172:173], 0, s[98:99]
	v_mfma_f32_32x32x16_bf16 v[18:33], v[184:187], v[188:191], v[18:33]
	s_add_u32 m0, s22, 0x5000
	s_nop 0
	global_load_lds_dwordx4 v[166:167], off
	v_lshl_add_u64 v[166:167], v[166:167], 0, s[98:99]
	v_mfma_f32_32x32x16_bf16 v[2:17], v[184:187], v[192:195], v[2:17]
	ds_read_b128 v[180:183], v122
	ds_read_b128 v[184:187], v122 offset:4096
	ds_read_b128 v[188:191], v224 offset:32768
	ds_read_b128 v[192:195], v224 offset:40960
	s_waitcnt lgkmcnt(4)
	v_mfma_f32_32x32x16_bf16 v[50:65], v[206:209], v[214:217], v[50:65]
	s_add_u32 m0, s22, 0xd000
	s_nop 0
	global_load_lds_dwordx4 v[174:175], off
	v_lshl_add_u64 v[174:175], v[174:175], 0, s[98:99]
	v_mfma_f32_32x32x16_bf16 v[34:49], v[206:209], v[218:221], v[34:49]
	s_add_u32 m0, s22, 0x6000
	s_nop 0
	global_load_lds_dwordx4 v[168:169], off
	v_lshl_add_u64 v[168:169], v[168:169], 0, s[98:99]
	v_mfma_f32_32x32x16_bf16 v[18:33], v[210:213], v[214:217], v[18:33]
	s_add_u32 m0, s22, 0xe000
	s_nop 0
	global_load_lds_dwordx4 v[176:177], off
	v_lshl_add_u64 v[176:177], v[176:177], 0, s[98:99]
	v_mfma_f32_32x32x16_bf16 v[2:17], v[210:213], v[218:221], v[2:17]
	ds_read_b128 v[206:209], v123
	ds_read_b128 v[210:213], v123 offset:4096
	ds_read_b128 v[214:217], v225 offset:32768
	ds_read_b128 v[218:221], v225 offset:40960
	s_waitcnt lgkmcnt(4)
	v_mfma_f32_32x32x16_bf16 v[50:65], v[180:183], v[188:191], v[50:65]
	s_add_u32 m0, s22, 0x7000
	s_nop 0
	global_load_lds_dwordx4 v[170:171], off
	v_lshl_add_u64 v[170:171], v[170:171], 0, s[98:99]
	v_mfma_f32_32x32x16_bf16 v[34:49], v[180:183], v[192:195], v[34:49]
	s_add_u32 m0, s22, 0xf000
	s_nop 0
	global_load_lds_dwordx4 v[178:179], off
	v_lshl_add_u64 v[178:179], v[178:179], 0, s[98:99]
	v_mfma_f32_32x32x16_bf16 v[18:33], v[184:187], v[188:191], v[18:33]
	v_mfma_f32_32x32x16_bf16 v[2:17], v[184:187], v[192:195], v[2:17]
	s_waitcnt vmcnt(0) lgkmcnt(0)
	s_barrier
	ds_read_b128 v[180:183], v120 offset:16384
	ds_read_b128 v[184:187], v120 offset:20480
	ds_read_b128 v[188:191], v222 offset:49152
	ds_read_b128 v[192:195], v222 offset:57344
	v_mfma_f32_32x32x16_bf16 v[50:65], v[206:209], v[214:217], v[50:65]
	v_mfma_f32_32x32x16_bf16 v[34:49], v[206:209], v[218:221], v[34:49]
	v_mfma_f32_32x32x16_bf16 v[18:33], v[210:213], v[214:217], v[18:33]
	v_mfma_f32_32x32x16_bf16 v[2:17], v[210:213], v[218:221], v[2:17]
	ds_read_b128 v[206:209], v121 offset:16384
	ds_read_b128 v[210:213], v121 offset:20480
	ds_read_b128 v[214:217], v223 offset:49152
	ds_read_b128 v[218:221], v223 offset:57344
	s_waitcnt lgkmcnt(4)
	v_mfma_f32_32x32x16_bf16 v[50:65], v[180:183], v[188:191], v[50:65]
	v_mfma_f32_32x32x16_bf16 v[34:49], v[180:183], v[192:195], v[34:49]
	v_mfma_f32_32x32x16_bf16 v[18:33], v[184:187], v[188:191], v[18:33]
	v_mfma_f32_32x32x16_bf16 v[2:17], v[184:187], v[192:195], v[2:17]
	ds_read_b128 v[180:183], v122 offset:16384
	ds_read_b128 v[184:187], v122 offset:20480
	ds_read_b128 v[188:191], v224 offset:49152
	ds_read_b128 v[192:195], v224 offset:57344
	s_waitcnt lgkmcnt(4)
	v_mfma_f32_32x32x16_bf16 v[50:65], v[206:209], v[214:217], v[50:65]
	v_mfma_f32_32x32x16_bf16 v[34:49], v[206:209], v[218:221], v[34:49]
	v_mfma_f32_32x32x16_bf16 v[18:33], v[210:213], v[214:217], v[18:33]
	v_mfma_f32_32x32x16_bf16 v[2:17], v[210:213], v[218:221], v[2:17]
	ds_read_b128 v[206:209], v123 offset:16384
	ds_read_b128 v[210:213], v123 offset:20480
	ds_read_b128 v[214:217], v225 offset:49152
	ds_read_b128 v[218:221], v225 offset:57344
	s_waitcnt lgkmcnt(4)
	v_mfma_f32_32x32x16_bf16 v[50:65], v[180:183], v[188:191], v[50:65]
	v_mfma_f32_32x32x16_bf16 v[34:49], v[180:183], v[192:195], v[34:49]
	v_mfma_f32_32x32x16_bf16 v[18:33], v[184:187], v[188:191], v[18:33]
	v_mfma_f32_32x32x16_bf16 v[2:17], v[184:187], v[192:195], v[2:17]
	s_waitcnt vmcnt(0) lgkmcnt(0)
	s_barrier
	v_mfma_f32_32x32x16_bf16 v[50:65], v[206:209], v[214:217], v[50:65]
	v_mfma_f32_32x32x16_bf16 v[34:49], v[206:209], v[218:221], v[34:49]
	v_mfma_f32_32x32x16_bf16 v[18:33], v[210:213], v[214:217], v[18:33]
	v_mfma_f32_32x32x16_bf16 v[2:17], v[210:213], v[218:221], v[2:17]
	s_nop 15
	v_add_u32_e32 v72, s0, v81
	v_or_b32_e32 v70, s1, v84
	s_movk_i32 s0, 0xa30
	v_or_b32_e32 v133, v72, v82
	v_or_b32_e32 v132, v72, v86
	v_or_b32_e32 v130, v72, v87
	v_or_b32_e32 v129, v72, v88
	v_or_b32_e32 v128, v72, v89
	v_or_b32_e32 v127, v72, v90
	v_or_b32_e32 v125, v72, v91
	v_or_b32_e32 v79, v72, v92
	v_ashrrev_i32_e32 v71, 31, v70
	v_or_b32_e32 v126, v72, v94
	v_or_b32_e32 v124, v72, v95
	v_or_b32_e32 v78, v72, v96
	v_or_b32_e32 v73, v72, v100
	v_cmp_gt_i32_e32 vcc, s0, v70
	v_or_b32_e32 v77, v72, v93
	v_or_b32_e32 v76, v72, v97
	v_or_b32_e32 v75, v72, v98
	v_or_b32_e32 v74, v72, v99
	s_and_saveexec_b64 s[0:1], vcc
	s_cbranch_execz .LBB0_493
	v_lshl_add_u64 v[134:135], v[70:71], 2, s[8:9]
	v_mad_i64_i32 v[136:137], s[4:5], v133, s15, v[134:135]
	s_nop 6
	global_store_dword v[136:137], v50, off sc1
	v_mad_i64_i32 v[136:137], s[4:5], v132, s15, v[134:135]
	global_store_dword v[136:137], v51, off sc1
	v_mad_i64_i32 v[50:51], s[4:5], v130, s15, v[134:135]
	global_store_dword v[50:51], v52, off sc1
	v_mad_i64_i32 v[50:51], s[4:5], v129, s15, v[134:135]
	global_store_dword v[50:51], v53, off sc1
	v_mad_i64_i32 v[50:51], s[4:5], v128, s15, v[134:135]
	global_store_dword v[50:51], v54, off sc1
	v_mad_i64_i32 v[50:51], s[4:5], v127, s15, v[134:135]
	global_store_dword v[50:51], v55, off sc1
	v_mad_i64_i32 v[50:51], s[4:5], v125, s15, v[134:135]
	global_store_dword v[50:51], v56, off sc1
	v_mad_i64_i32 v[50:51], s[4:5], v79, s15, v[134:135]
	global_store_dword v[50:51], v57, off sc1
	v_mad_i64_i32 v[50:51], s[4:5], v77, s15, v[134:135]
	global_store_dword v[50:51], v58, off sc1
	v_mad_i64_i32 v[50:51], s[4:5], v126, s15, v[134:135]
	global_store_dword v[50:51], v59, off sc1
	v_mad_i64_i32 v[50:51], s[4:5], v124, s15, v[134:135]
	global_store_dword v[50:51], v60, off sc1
	v_mad_i64_i32 v[50:51], s[4:5], v78, s15, v[134:135]
	global_store_dword v[50:51], v61, off sc1
	v_mad_i64_i32 v[50:51], s[4:5], v76, s15, v[134:135]
	global_store_dword v[50:51], v62, off sc1
	v_mad_i64_i32 v[50:51], s[4:5], v75, s15, v[134:135]
	global_store_dword v[50:51], v63, off sc1
	v_mad_i64_i32 v[50:51], s[4:5], v74, s15, v[134:135]
	global_store_dword v[50:51], v64, off sc1
	v_mad_i64_i32 v[50:51], s[4:5], v73, s15, v[134:135]
	global_store_dword v[50:51], v65, off sc1
